# phase B GEMM K-loop: two of the six SP2 LDS-DMA issues moved from the load segment into the MFMA block, vmcnt 8 to 6
# baseline (speedup 1.0000x reference)
; #define PG8_STAGE(bufoff, gbase, voff) do { _Pragma("unroll") for (int _i = 0; _i < 2; ++_i) \
;         __builtin_amdgcn_global_load_lds((const unsigned*)((const char*)(gbase) + (voff)[_i]), (PG8_LAS unsigned*)(lds + (bufoff) + ldsw + _i * 8192), 16, 0, 0); } while (0)
; #define PG8_LDA(dst, b, h) do { _Pragma("unroll") for (int m = 0; m < 4; ++m) _Pragma("unroll") for (int k = 0; k < 2; ++k) dst[m][k] = *(const PG8_LAS bf16x8*)(lds + PG8_SA(b, h) + aoff + m * 2048 + k * 1024); } while (0)
; #define PG8_LDB(dst, b, h) do { _Pragma("unroll") for (int n = 0; n < 2; ++n) _Pragma("unroll") for (int k = 0; k < 2; ++k) dst[n][k] = *(const PG8_LAS bf16x8*)(lds + PG8_SB(b, h) + boff + n * 2048 + k * 1024); } while (0)
; #define PG8_MMA(ai, bj, At, Bt) do { __builtin_amdgcn_s_setprio(1); _Pragma("unroll") for (int m = 0; m < 4; ++m) _Pragma("unroll") for (int n = 0; n < 2; ++n) _Pragma("unroll") for (int k = 0; k < 2; ++k) \
;         acc[ai][bj][m][n] = __builtin_amdgcn_mfma_f32_16x16x32_bf16(Bt[n][k], At[m][k], acc[ai][bj][m][n], 0, 0, 0); __builtin_amdgcn_s_setprio(0); } while (0)
; #define PG8_WAIT_V(n) asm volatile("s_waitcnt vmcnt(" #n ")" ::: "memory")
; #define PG8_WAIT_L(n) asm volatile("s_waitcnt lgkmcnt(" #n ")" ::: "memory")
; #define PG8_BAR __builtin_amdgcn_s_barrier()
; #define PG8_SCHED __builtin_amdgcn_sched_barrier(0)
; template <class Epi, class Sched, bool ALIGN_EPI = false, bool SP2 = false, class Hook = NoHook>
; __device__ __forceinline__ void gemm_phase(PG8_LAS unsigned char* lds, const Gemm g, const Sched& S, const Epi& E, int tid, const Hook& H = Hook()) {
;     ...
;             PG8_LDB(B0, 0, 0); PG8_LDB(B1, 0, 1); PG8_SCHED; PG8_LDA(At, 0, 0); PG8_STAGE(PG8_SA(1, 1), a1 + hstep, voffA);
;             PG8_WAIT_V(8); PG8_WAIT_L(0); PG8_BAR; PG8_MMA(0, 0, At, B0); PG8_MMA(0, 1, At, B1); PG8_BAR; PG8_SCHED;
;             PG8_LDA(At, 0, 1); PG8_STAGE(PG8_SB(0, 0), b2, voffB); PG8_STAGE(PG8_SB(0, 1), b2 + hstep, voffB); PG8_STAGE(PG8_SA(0, 0), a2, voffA);
.LBB0_343:
	s_add_u32 s42, s0, 0xfffc0080
	s_addc_u32 s43, s1, -1
	s_add_i32 s76, 0, 0x10000
	s_cmp_eq_u32 s75, 12
	s_cselect_b32 s47, s35, s43
	s_cselect_b32 s46, s45, s42
	v_add_u32_e32 v96, s76, v231
	s_cselect_b32 s43, s55, s74
	s_cselect_b32 s42, s72, s73
	s_add_i32 s83, 0, 0x14000
	ds_read_b128 v[130:133], v96
	ds_read_b128 v[134:137], v96 offset:1024
	ds_read_b128 v[138:141], v96 offset:2048
	ds_read_b128 v[150:153], v96 offset:3072
	v_add_u32_e32 v96, s83, v231
	ds_read_b128 v[154:157], v96
	ds_read_b128 v[158:161], v96 offset:1024
	ds_read_b128 v[162:165], v96 offset:2048
	ds_read_b128 v[166:169], v96 offset:3072
	v_lshl_add_u64 v[202:203], s[0:1], 0, v[146:147]
	s_add_i32 m0, s26, 0xc000
	ds_read_b128 v[170:173], v232
	ds_read_b128 v[174:177], v232 offset:1024
	ds_read_b128 v[178:181], v232 offset:2048
	ds_read_b128 v[182:185], v232 offset:3072
	ds_read_b128 v[186:189], v232 offset:4096
	ds_read_b128 v[190:193], v232 offset:5120
	ds_read_b128 v[194:197], v232 offset:6144
	ds_read_b128 v[198:201], v232 offset:7168
	global_load_lds_dwordx4 v[202:203], off
	v_lshl_add_u64 v[202:203], s[0:1], 0, v[148:149]
	s_add_i32 m0, s26, 0xe000
	s_nop 0
	global_load_lds_dwordx4 v[202:203], off
	s_waitcnt vmcnt(8)
	s_waitcnt lgkmcnt(0)
	s_barrier
	s_setprio 1
	s_waitcnt lgkmcnt(0)
	v_mfma_f32_16x16x32_bf16 v[126:129], v[130:133], v[170:173], v[126:129]
	v_mfma_f32_16x16x32_bf16 v[122:125], v[138:141], v[170:173], v[122:125]
	v_mfma_f32_16x16x32_bf16 v[110:113], v[130:133], v[178:181], v[110:113]
	v_mfma_f32_16x16x32_bf16 v[106:109], v[138:141], v[178:181], v[106:109]
	v_mfma_f32_16x16x32_bf16 v[92:95], v[130:133], v[186:189], v[92:95]
	v_mfma_f32_16x16x32_bf16 v[88:91], v[138:141], v[186:189], v[88:91]
	v_mfma_f32_16x16x32_bf16 v[76:79], v[130:133], v[194:197], v[76:79]
	v_mfma_f32_16x16x32_bf16 v[72:75], v[138:141], v[194:197], v[72:75]
	v_mfma_f32_16x16x32_bf16 v[126:129], v[134:137], v[174:177], v[126:129]
	v_mfma_f32_16x16x32_bf16 v[122:125], v[150:153], v[174:177], v[122:125]
	v_mfma_f32_16x16x32_bf16 v[110:113], v[134:137], v[182:185], v[110:113]
	v_mfma_f32_16x16x32_bf16 v[106:109], v[150:153], v[182:185], v[106:109]
	v_mfma_f32_16x16x32_bf16 v[92:95], v[134:137], v[190:193], v[92:95]
	v_mfma_f32_16x16x32_bf16 v[88:91], v[150:153], v[190:193], v[88:91]
	v_mfma_f32_16x16x32_bf16 v[76:79], v[134:137], v[198:201], v[76:79]
	v_mfma_f32_16x16x32_bf16 v[72:75], v[150:153], v[198:201], v[72:75]
	s_setprio 0
	s_setprio 1
	v_mfma_f32_16x16x32_bf16 v[118:121], v[154:157], v[170:173], v[118:121]
	v_mfma_f32_16x16x32_bf16 v[114:117], v[162:165], v[170:173], v[114:117]
	v_mfma_f32_16x16x32_bf16 v[102:105], v[154:157], v[178:181], v[102:105]
	v_mfma_f32_16x16x32_bf16 v[98:101], v[162:165], v[178:181], v[98:101]
	v_mfma_f32_16x16x32_bf16 v[84:87], v[154:157], v[186:189], v[84:87]
	v_mfma_f32_16x16x32_bf16 v[80:83], v[162:165], v[186:189], v[80:83]
	v_mfma_f32_16x16x32_bf16 v[68:71], v[154:157], v[194:197], v[68:71]
	v_mfma_f32_16x16x32_bf16 v[64:67], v[162:165], v[194:197], v[64:67]
	v_mfma_f32_16x16x32_bf16 v[118:121], v[158:161], v[174:177], v[118:121]
	v_mfma_f32_16x16x32_bf16 v[114:117], v[166:169], v[174:177], v[114:117]
	v_mfma_f32_16x16x32_bf16 v[102:105], v[158:161], v[182:185], v[102:105]
	v_mfma_f32_16x16x32_bf16 v[98:101], v[166:169], v[182:185], v[98:101]
	v_mfma_f32_16x16x32_bf16 v[84:87], v[158:161], v[190:193], v[84:87]
	v_mfma_f32_16x16x32_bf16 v[80:83], v[166:169], v[190:193], v[80:83]
	v_mfma_f32_16x16x32_bf16 v[68:71], v[158:161], v[198:201], v[68:71]
	v_mfma_f32_16x16x32_bf16 v[64:67], v[166:169], v[198:201], v[64:67]
	s_setprio 0
	s_barrier
	s_add_i32 s76, s76, s24
	v_lshl_add_u64 v[202:203], s[42:43], 0, v[142:143]
	s_mov_b32 m0, s76
	ds_read_b128 v[170:173], v232 offset:16384
	ds_read_b128 v[174:177], v232 offset:17408
	ds_read_b128 v[178:181], v232 offset:18432
	ds_read_b128 v[182:185], v232 offset:19456
	ds_read_b128 v[186:189], v232 offset:20480
	ds_read_b128 v[190:193], v232 offset:21504
	ds_read_b128 v[194:197], v232 offset:22528
	ds_read_b128 v[198:201], v232 offset:23552
	global_load_lds_dwordx4 v[202:203], off
	s_add_i32 m0, s76, 0x2000
	s_add_u32 s76, s42, 0x40000
	v_lshl_add_u64 v[204:205], s[42:43], 0, v[144:145]
	s_addc_u32 s77, s43, 0
	s_add_i32 s83, s83, s24
	global_load_lds_dwordx4 v[204:205], off
	v_lshl_add_u64 v[206:207], s[76:77], 0, v[142:143]
	s_mov_b32 m0, s83
	v_lshl_add_u64 v[208:209], s[46:47], 0, v[144:145]
	global_load_lds_dwordx4 v[206:207], off
	v_lshl_add_u64 v[206:207], s[76:77], 0, v[144:145]
	s_add_i32 m0, s83, 0x2000
	s_nop 0
	global_load_lds_dwordx4 v[206:207], off
	v_lshl_add_u64 v[206:207], s[46:47], 0, v[142:143]
	s_waitcnt vmcnt(6)
	s_waitcnt lgkmcnt(0)
	s_barrier
; #define PG8_STAGE(bufoff, gbase, voff) do { _Pragma("unroll") for (int _i = 0; _i < 2; ++_i) \
;         __builtin_amdgcn_global_load_lds((const unsigned*)((const char*)(gbase) + (voff)[_i]), (PG8_LAS unsigned*)(lds + (bufoff) + ldsw + _i * 8192), 16, 0, 0); } while (0)
; #define PG8_LDA(dst, b, h) do { _Pragma("unroll") for (int m = 0; m < 4; ++m) _Pragma("unroll") for (int k = 0; k < 2; ++k) dst[m][k] = *(const PG8_LAS bf16x8*)(lds + PG8_SA(b, h) + aoff + m * 2048 + k * 1024); } while (0)
; #define PG8_LDB(dst, b, h) do { _Pragma("unroll") for (int n = 0; n < 2; ++n) _Pragma("unroll") for (int k = 0; k < 2; ++k) dst[n][k] = *(const PG8_LAS bf16x8*)(lds + PG8_SB(b, h) + boff + n * 2048 + k * 1024); } while (0)
; #define PG8_MMA(ai, bj, At, Bt) do { __builtin_amdgcn_s_setprio(1); _Pragma("unroll") for (int m = 0; m < 4; ++m) _Pragma("unroll") for (int n = 0; n < 2; ++n) _Pragma("unroll") for (int k = 0; k < 2; ++k) \
;         acc[ai][bj][m][n] = __builtin_amdgcn_mfma_f32_16x16x32_bf16(Bt[n][k], At[m][k], acc[ai][bj][m][n], 0, 0, 0); __builtin_amdgcn_s_setprio(0); } while (0)
; #define PG8_WAIT_V(n) asm volatile("s_waitcnt vmcnt(" #n ")" ::: "memory")
; #define PG8_WAIT_L(n) asm volatile("s_waitcnt lgkmcnt(" #n ")" ::: "memory")
; #define PG8_BAR __builtin_amdgcn_s_barrier()
; #define PG8_SCHED __builtin_amdgcn_sched_barrier(0)
; template <class Epi, class Sched, bool ALIGN_EPI = false, bool SP2 = false, class Hook = NoHook>
; __device__ __forceinline__ void gemm_phase(PG8_LAS unsigned char* lds, const Gemm g, const Sched& S, const Epi& E, int tid, const Hook& H = Hook()) {
;     ...
;             PG8_WAIT_V(8); PG8_WAIT_L(0); PG8_BAR; PG8_MMA(1, 0, At, B0); PG8_MMA(1, 1, At, B1); PG8_BAR; PG8_SCHED;
;             PG8_LDB(B0, 1, 0); PG8_LDB(B1, 1, 1); PG8_SCHED; PG8_LDA(At, 1, 0); PG8_STAGE(PG8_SA(0, 1), a2 + hstep, voffA);
;             PG8_WAIT_V(8); PG8_WAIT_L(0); PG8_BAR; PG8_MMA(0, 0, At, B0); PG8_MMA(0, 1, At, B1); PG8_BAR; PG8_SCHED;
	s_setprio 1
	s_waitcnt lgkmcnt(0)
	v_mfma_f32_16x16x32_bf16 v[60:63], v[130:133], v[170:173], v[60:63]
	v_mfma_f32_16x16x32_bf16 v[56:59], v[138:141], v[170:173], v[56:59]
	v_mfma_f32_16x16x32_bf16 v[44:47], v[130:133], v[178:181], v[44:47]
	v_mfma_f32_16x16x32_bf16 v[40:43], v[138:141], v[178:181], v[40:43]
	v_mfma_f32_16x16x32_bf16 v[28:31], v[130:133], v[186:189], v[28:31]
	v_mfma_f32_16x16x32_bf16 v[24:27], v[138:141], v[186:189], v[24:27]
	v_mfma_f32_16x16x32_bf16 v[12:15], v[130:133], v[194:197], v[12:15]
	v_mfma_f32_16x16x32_bf16 v[8:11], v[138:141], v[194:197], v[8:11]
	s_mov_b32 m0, s26
	v_mfma_f32_16x16x32_bf16 v[60:63], v[134:137], v[174:177], v[60:63]
	global_load_lds_dwordx4 v[206:207], off
	v_mfma_f32_16x16x32_bf16 v[56:59], v[150:153], v[174:177], v[56:59]
	v_mfma_f32_16x16x32_bf16 v[44:47], v[134:137], v[182:185], v[44:47]
	v_mfma_f32_16x16x32_bf16 v[40:43], v[150:153], v[182:185], v[40:43]
	v_mfma_f32_16x16x32_bf16 v[28:31], v[134:137], v[190:193], v[28:31]
	v_mfma_f32_16x16x32_bf16 v[24:27], v[150:153], v[190:193], v[24:27]
	v_mfma_f32_16x16x32_bf16 v[12:15], v[134:137], v[198:201], v[12:15]
	v_mfma_f32_16x16x32_bf16 v[8:11], v[150:153], v[198:201], v[8:11]
	s_setprio 0
	s_setprio 1
	v_mfma_f32_16x16x32_bf16 v[52:55], v[154:157], v[170:173], v[52:55]
	v_mfma_f32_16x16x32_bf16 v[48:51], v[162:165], v[170:173], v[48:51]
	v_mfma_f32_16x16x32_bf16 v[36:39], v[154:157], v[178:181], v[36:39]
	v_mfma_f32_16x16x32_bf16 v[32:35], v[162:165], v[178:181], v[32:35]
	s_mov_b32 m0, s27
	v_mfma_f32_16x16x32_bf16 v[20:23], v[154:157], v[186:189], v[20:23]
	global_load_lds_dwordx4 v[208:209], off
	v_mfma_f32_16x16x32_bf16 v[16:19], v[162:165], v[186:189], v[16:19]
	v_mfma_f32_16x16x32_bf16 v[4:7], v[154:157], v[194:197], v[4:7]
	v_mfma_f32_16x16x32_bf16 v[0:3], v[162:165], v[194:197], v[0:3]
	v_mfma_f32_16x16x32_bf16 v[52:55], v[158:161], v[174:177], v[52:55]
	v_mfma_f32_16x16x32_bf16 v[48:51], v[166:169], v[174:177], v[48:51]
	v_mfma_f32_16x16x32_bf16 v[36:39], v[158:161], v[182:185], v[36:39]
	v_mfma_f32_16x16x32_bf16 v[32:35], v[166:169], v[182:185], v[32:35]
	v_mfma_f32_16x16x32_bf16 v[20:23], v[158:161], v[190:193], v[20:23]
	v_mfma_f32_16x16x32_bf16 v[16:19], v[166:169], v[190:193], v[16:19]
	v_mfma_f32_16x16x32_bf16 v[4:7], v[158:161], v[198:201], v[4:7]
	v_mfma_f32_16x16x32_bf16 v[0:3], v[166:169], v[198:201], v[0:3]
	s_setprio 0
	s_barrier
	s_add_i32 s76, 0, 0x18000
	v_add_u32_e32 v96, s76, v231
	s_add_i32 s77, 0, 0x1c000
	ds_read_b128 v[130:133], v96
	ds_read_b128 v[134:137], v96 offset:1024
	ds_read_b128 v[138:141], v96 offset:2048
	ds_read_b128 v[150:153], v96 offset:3072
	v_add_u32_e32 v96, s77, v231
	ds_read_b128 v[154:157], v96
	ds_read_b128 v[158:161], v96 offset:1024
	ds_read_b128 v[162:165], v96 offset:2048
	ds_read_b128 v[166:169], v96 offset:3072
	s_add_u32 s46, s46, 0x40000
	s_addc_u32 s47, s47, 0
	s_mov_b32 m0, s58
	v_lshl_add_u64 v[234:235], s[46:47], 0, v[142:143]
	ds_read_b128 v[170:173], v232 offset:32768
	ds_read_b128 v[174:177], v232 offset:33792
	ds_read_b128 v[178:181], v232 offset:34816
	ds_read_b128 v[182:185], v232 offset:35840
	ds_read_b128 v[186:189], v232 offset:36864
	ds_read_b128 v[190:193], v232 offset:37888
	ds_read_b128 v[194:197], v232 offset:38912
	ds_read_b128 v[198:201], v232 offset:39936
	global_load_lds_dwordx4 v[234:235], off
	v_lshl_add_u64 v[234:235], s[46:47], 0, v[144:145]
	s_mov_b32 m0, s59
	s_nop 0
	global_load_lds_dwordx4 v[234:235], off
	s_waitcnt vmcnt(8)
	s_waitcnt lgkmcnt(0)
	s_barrier
	s_setprio 1
	s_waitcnt lgkmcnt(0)
	v_mfma_f32_16x16x32_bf16 v[126:129], v[130:133], v[170:173], v[126:129]
	v_mfma_f32_16x16x32_bf16 v[122:125], v[138:141], v[170:173], v[122:125]
	v_mfma_f32_16x16x32_bf16 v[110:113], v[130:133], v[178:181], v[110:113]
	v_mfma_f32_16x16x32_bf16 v[106:109], v[138:141], v[178:181], v[106:109]
	v_mfma_f32_16x16x32_bf16 v[92:95], v[130:133], v[186:189], v[92:95]
	v_mfma_f32_16x16x32_bf16 v[88:91], v[138:141], v[186:189], v[88:91]
	v_mfma_f32_16x16x32_bf16 v[76:79], v[130:133], v[194:197], v[76:79]
	v_mfma_f32_16x16x32_bf16 v[72:75], v[138:141], v[194:197], v[72:75]
	v_mfma_f32_16x16x32_bf16 v[126:129], v[134:137], v[174:177], v[126:129]
	v_mfma_f32_16x16x32_bf16 v[122:125], v[150:153], v[174:177], v[122:125]
	v_mfma_f32_16x16x32_bf16 v[110:113], v[134:137], v[182:185], v[110:113]
	v_mfma_f32_16x16x32_bf16 v[106:109], v[150:153], v[182:185], v[106:109]
	v_mfma_f32_16x16x32_bf16 v[92:95], v[134:137], v[190:193], v[92:95]
	v_mfma_f32_16x16x32_bf16 v[88:91], v[150:153], v[190:193], v[88:91]
	v_mfma_f32_16x16x32_bf16 v[76:79], v[134:137], v[198:201], v[76:79]
	v_mfma_f32_16x16x32_bf16 v[72:75], v[150:153], v[198:201], v[72:75]
	s_setprio 0
	s_setprio 1
	v_mfma_f32_16x16x32_bf16 v[118:121], v[154:157], v[170:173], v[118:121]
	v_mfma_f32_16x16x32_bf16 v[114:117], v[162:165], v[170:173], v[114:117]
	v_mfma_f32_16x16x32_bf16 v[102:105], v[154:157], v[178:181], v[102:105]
	v_mfma_f32_16x16x32_bf16 v[98:101], v[162:165], v[178:181], v[98:101]
	v_mfma_f32_16x16x32_bf16 v[84:87], v[154:157], v[186:189], v[84:87]
	v_mfma_f32_16x16x32_bf16 v[80:83], v[162:165], v[186:189], v[80:83]
	v_mfma_f32_16x16x32_bf16 v[68:71], v[154:157], v[194:197], v[68:71]
	v_mfma_f32_16x16x32_bf16 v[64:67], v[162:165], v[194:197], v[64:67]
	v_mfma_f32_16x16x32_bf16 v[118:121], v[158:161], v[174:177], v[118:121]
	v_mfma_f32_16x16x32_bf16 v[114:117], v[166:169], v[174:177], v[114:117]
	v_mfma_f32_16x16x32_bf16 v[102:105], v[158:161], v[182:185], v[102:105]
	v_mfma_f32_16x16x32_bf16 v[98:101], v[166:169], v[182:185], v[98:101]
	v_mfma_f32_16x16x32_bf16 v[84:87], v[158:161], v[190:193], v[84:87]
	v_mfma_f32_16x16x32_bf16 v[80:83], v[166:169], v[190:193], v[80:83]
	v_mfma_f32_16x16x32_bf16 v[68:71], v[158:161], v[198:201], v[68:71]
	v_mfma_f32_16x16x32_bf16 v[64:67], v[166:169], v[198:201], v[64:67]
	s_setprio 0
	s_barrier
; #define PG8_STAGE(bufoff, gbase, voff) do { _Pragma("unroll") for (int _i = 0; _i < 2; ++_i) \
;         __builtin_amdgcn_global_load_lds((const unsigned*)((const char*)(gbase) + (voff)[_i]), (PG8_LAS unsigned*)(lds + (bufoff) + ldsw + _i * 8192), 16, 0, 0); } while (0)
; #define PG8_LDA(dst, b, h) do { _Pragma("unroll") for (int m = 0; m < 4; ++m) _Pragma("unroll") for (int k = 0; k < 2; ++k) dst[m][k] = *(const PG8_LAS bf16x8*)(lds + PG8_SA(b, h) + aoff + m * 2048 + k * 1024); } while (0)
; #define PG8_MMA(ai, bj, At, Bt) do { __builtin_amdgcn_s_setprio(1); _Pragma("unroll") for (int m = 0; m < 4; ++m) _Pragma("unroll") for (int n = 0; n < 2; ++n) _Pragma("unroll") for (int k = 0; k < 2; ++k) \
;         acc[ai][bj][m][n] = __builtin_amdgcn_mfma_f32_16x16x32_bf16(Bt[n][k], At[m][k], acc[ai][bj][m][n], 0, 0, 0); __builtin_amdgcn_s_setprio(0); } while (0)
; #define PG8_WAIT_V(n) asm volatile("s_waitcnt vmcnt(" #n ")" ::: "memory")
; #define PG8_WAIT_L(n) asm volatile("s_waitcnt lgkmcnt(" #n ")" ::: "memory")
; #define PG8_BAR __builtin_amdgcn_s_barrier()
; #define PG8_SCHED __builtin_amdgcn_sched_barrier(0)
; template <class Epi, class Sched, bool ALIGN_EPI = false, bool SP2 = false, class Hook = NoHook>
; __device__ __forceinline__ void gemm_phase(PG8_LAS unsigned char* lds, const Gemm g, const Sched& S, const Epi& E, int tid, const Hook& H = Hook()) {
;     ...
;             PG8_LDA(At, 1, 1); PG8_STAGE(PG8_SB(1, 0), b3, voffB); PG8_STAGE(PG8_SB(1, 1), b3 + hstep, voffB); PG8_STAGE(PG8_SA(1, 0), a3, voffA);
;             PG8_WAIT_V(8); PG8_WAIT_L(0); PG8_BAR; PG8_MMA(1, 0, At, B0); PG8_MMA(1, 1, At, B1); PG8_BAR; PG8_SCHED;
	s_add_i32 s46, s76, s24
	v_lshl_add_u64 v[202:203], v[202:203], 0, s[4:5]
	s_mov_b32 m0, s46
	ds_read_b128 v[170:173], v232 offset:49152
	ds_read_b128 v[174:177], v232 offset:50176
	ds_read_b128 v[178:181], v232 offset:51200
	ds_read_b128 v[182:185], v232 offset:52224
	ds_read_b128 v[186:189], v232 offset:53248
	ds_read_b128 v[190:193], v232 offset:54272
	ds_read_b128 v[194:197], v232 offset:55296
	ds_read_b128 v[198:201], v232 offset:56320
	global_load_lds_dwordx4 v[202:203], off
	s_add_i32 m0, s46, 0x2000
	s_add_u32 s42, s42, 0x40080
	v_lshl_add_u64 v[202:203], v[204:205], 0, s[4:5]
	s_addc_u32 s43, s43, 0
	s_add_i32 s46, s77, s24
	global_load_lds_dwordx4 v[202:203], off
	v_lshl_add_u64 v[202:203], s[42:43], 0, v[142:143]
	s_mov_b32 m0, s46
	s_nop 0
	global_load_lds_dwordx4 v[202:203], off
	v_lshl_add_u64 v[202:203], s[42:43], 0, v[144:145]
	s_add_i32 m0, s46, 0x2000
	s_nop 0
	global_load_lds_dwordx4 v[202:203], off
	s_waitcnt vmcnt(6)
	s_waitcnt lgkmcnt(0)
	s_barrier
	s_setprio 1
	s_waitcnt lgkmcnt(0)
	v_mfma_f32_16x16x32_bf16 v[60:63], v[130:133], v[170:173], v[60:63]
	v_mfma_f32_16x16x32_bf16 v[56:59], v[138:141], v[170:173], v[56:59]
	v_mfma_f32_16x16x32_bf16 v[44:47], v[130:133], v[178:181], v[44:47]
	v_mfma_f32_16x16x32_bf16 v[40:43], v[138:141], v[178:181], v[40:43]
	v_mfma_f32_16x16x32_bf16 v[28:31], v[130:133], v[186:189], v[28:31]
	v_mfma_f32_16x16x32_bf16 v[24:27], v[138:141], v[186:189], v[24:27]
	v_mfma_f32_16x16x32_bf16 v[12:15], v[130:133], v[194:197], v[12:15]
	v_mfma_f32_16x16x32_bf16 v[8:11], v[138:141], v[194:197], v[8:11]
	v_lshl_add_u64 v[202:203], v[206:207], 0, s[4:5]
	s_mov_b32 m0, s65
	v_mfma_f32_16x16x32_bf16 v[60:63], v[134:137], v[174:177], v[60:63]
	global_load_lds_dwordx4 v[202:203], off
	v_mfma_f32_16x16x32_bf16 v[56:59], v[150:153], v[174:177], v[56:59]
	v_mfma_f32_16x16x32_bf16 v[44:47], v[134:137], v[182:185], v[44:47]
	v_mfma_f32_16x16x32_bf16 v[40:43], v[150:153], v[182:185], v[40:43]
	v_mfma_f32_16x16x32_bf16 v[28:31], v[134:137], v[190:193], v[28:31]
	v_mfma_f32_16x16x32_bf16 v[24:27], v[150:153], v[190:193], v[24:27]
	v_mfma_f32_16x16x32_bf16 v[12:15], v[134:137], v[198:201], v[12:15]
	v_mfma_f32_16x16x32_bf16 v[8:11], v[150:153], v[198:201], v[8:11]
	s_setprio 0
	s_setprio 1
	v_mfma_f32_16x16x32_bf16 v[52:55], v[154:157], v[170:173], v[52:55]
	v_mfma_f32_16x16x32_bf16 v[48:51], v[162:165], v[170:173], v[48:51]
	v_mfma_f32_16x16x32_bf16 v[36:39], v[154:157], v[178:181], v[36:39]
	v_mfma_f32_16x16x32_bf16 v[32:35], v[162:165], v[178:181], v[32:35]
	v_lshl_add_u64 v[202:203], v[208:209], 0, s[4:5]
	s_mov_b32 m0, s93
	v_mfma_f32_16x16x32_bf16 v[20:23], v[154:157], v[186:189], v[20:23]
	global_load_lds_dwordx4 v[202:203], off
	v_mfma_f32_16x16x32_bf16 v[16:19], v[162:165], v[186:189], v[16:19]
	v_mfma_f32_16x16x32_bf16 v[4:7], v[154:157], v[194:197], v[4:7]
	v_mfma_f32_16x16x32_bf16 v[0:3], v[162:165], v[194:197], v[0:3]
	v_mfma_f32_16x16x32_bf16 v[52:55], v[158:161], v[174:177], v[52:55]
	v_mfma_f32_16x16x32_bf16 v[48:51], v[166:169], v[174:177], v[48:51]
	v_mfma_f32_16x16x32_bf16 v[36:39], v[158:161], v[182:185], v[36:39]
	v_mfma_f32_16x16x32_bf16 v[32:35], v[166:169], v[182:185], v[32:35]
	v_mfma_f32_16x16x32_bf16 v[20:23], v[158:161], v[190:193], v[20:23]
	v_mfma_f32_16x16x32_bf16 v[16:19], v[166:169], v[190:193], v[16:19]
	v_mfma_f32_16x16x32_bf16 v[4:7], v[158:161], v[198:201], v[4:7]
	v_mfma_f32_16x16x32_bf16 v[0:3], v[166:169], v[198:201], v[0:3]
	s_setprio 0
	s_barrier
	s_add_i32 s75, s75, 2
	s_add_u32 s0, s0, 0x100
	s_addc_u32 s1, s1, 0
	s_add_u32 s73, s73, 0x100
	s_addc_u32 s74, s74, 0
	s_cmp_gt_u32 s75, 13
	s_cbranch_scc0 .LBB0_343
	s_and_b64 vcc, exec, s[18:19]
	s_cbranch_vccz .LBB0_346
	s_barrier
